# UP unit order: the sample-panel units (longer epilogue) moved onto workgroups that run five units (permutation inside the last row-panel group)
# speedup vs baseline: 1.0264x; 1.0038x over previous
.LBB0_1045:
	s_ashr_i32 s0, s0, 3
	s_add_i32 s0, s5, s0
	s_mul_hi_i32 s1, s0, 0x9c09c09d
	s_add_i32 s1, s1, s0
	s_lshr_b32 s5, s1, 31
	s_ashr_i32 s1, s1, 6
	s_add_i32 s1, s1, s5
	s_mul_i32 s5, s1, 5
	s_sub_i32 s24, 0x41, s5
	s_min_i32 s24, s24, 5
	s_abs_i32 s25, s24
	v_cvt_f32_u32_e32 v2, s25
	s_sub_i32 s38, 0, s25
	s_mulk_i32 s1, 0x69
	s_sub_i32 s0, s0, s1
	v_rcp_iflag_f32_e32 v2, v2
	s_abs_i32 s1, s0
	s_xor_b32 s35, s0, s24
	s_ashr_i32 s35, s35, 31
	v_mul_f32_e32 v2, 0x4f7ffffe, v2
	v_cvt_u32_f32_e32 v2, v2
	s_nop 0
	v_readfirstlane_b32 s39, v2
	s_mul_i32 s38, s38, s39
	s_mul_hi_u32 s38, s39, s38
	s_add_i32 s39, s39, s38
	s_mul_hi_u32 s38, s1, s39
	s_mul_i32 s39, s38, s25
	s_sub_i32 s1, s1, s39
	s_add_i32 s40, s38, 1
	s_sub_i32 s39, s1, s25
	s_cmp_ge_u32 s1, s25
	s_cselect_b32 s38, s40, s38
	s_cselect_b32 s1, s39, s1
	s_add_i32 s39, s38, 1
	s_cmp_ge_u32 s1, s25
	s_cselect_b32 s1, s39, s38
	s_xor_b32 s1, s1, s35
	s_sub_i32 s46, s1, s35
	s_mul_i32 s1, s46, s24
	s_sub_i32 s0, s0, s1
	s_add_i32 s48, s5, s0
	s_cmp_lt_i32 s48, 60
	s_cbranch_scc1 .Lup_remap_done
	s_sub_i32 s0, s48, 60
	s_mul_i32 s1, s46, 5
	s_add_i32 s0, s0, s1
	s_cmp_lt_i32 s0, 9
	s_cbranch_scc1 .Lup_remap_prompt
	s_cmp_lt_i32 s0, 30
	s_cbranch_scc0 .Lup_remap_p2
	s_mov_b32 s48, 64
	s_sub_i32 s46, s0, 9
	s_branch .Lup_remap_done
.Lup_remap_p2:
	s_sub_i32 s0, s0, 21
.Lup_remap_prompt:
	s_and_b32 s1, s0, 3
	s_add_i32 s48, s1, 60
	s_lshr_b32 s46, s0, 2
.Lup_remap_done:
.LBB0_1046:
	s_ashr_i32 s49, s48, 31
	s_lshl_b64 s[0:1], s[48:49], 19
	s_add_u32 s50, s29, s0
	s_addc_u32 s51, s56, s1
	s_and_b64 s[0:1], s[36:37], exec
	s_cselect_b32 s0, s51, s7
	s_cselect_b32 s1, s50, s6
	s_ashr_i32 s47, s46, 31
	s_lshl_b64 s[24:25], s[46:47], 19
	s_add_u32 s52, s57, s24
	s_addc_u32 s53, s58, s25
	s_and_b64 s[24:25], s[36:37], exec
	s_cselect_b32 s5, s53, s21
	s_cselect_b32 s35, s52, s20
	s_add_u32 s6, s6, 0x40080
	s_addc_u32 s7, s7, 0
	s_add_u32 s38, s20, 0x100
	v_mov_b32_e32 v2, 0
	s_addc_u32 s39, s21, 0
	s_mov_b32 s40, -2
	v_mov_b32_e32 v3, v2
	v_mov_b32_e32 v4, v2
	v_mov_b32_e32 v5, v2
	v_mov_b32_e32 v14, v2
	v_mov_b32_e32 v15, v2
	v_mov_b32_e32 v16, v2
	v_mov_b32_e32 v17, v2
	v_mov_b32_e32 v26, v2
	v_mov_b32_e32 v27, v2
	v_mov_b32_e32 v28, v2
	v_mov_b32_e32 v29, v2
	v_mov_b32_e32 v34, v2
	v_mov_b32_e32 v35, v2
	v_mov_b32_e32 v36, v2
	v_mov_b32_e32 v37, v2
	v_mov_b32_e32 v42, v2
	v_mov_b32_e32 v43, v2
	v_mov_b32_e32 v44, v2
	v_mov_b32_e32 v45, v2
	v_mov_b32_e32 v50, v2
	v_mov_b32_e32 v51, v2
	v_mov_b32_e32 v52, v2
	v_mov_b32_e32 v53, v2
	v_mov_b32_e32 v58, v2
	v_mov_b32_e32 v59, v2
	v_mov_b32_e32 v60, v2
	v_mov_b32_e32 v61, v2
	v_mov_b32_e32 v62, v2
	v_mov_b32_e32 v63, v2
	v_mov_b32_e32 v64, v2
	v_mov_b32_e32 v65, v2
	v_mov_b32_e32 v6, v2
	v_mov_b32_e32 v7, v2
	v_mov_b32_e32 v8, v2
	v_mov_b32_e32 v9, v2
	v_mov_b32_e32 v18, v2
	v_mov_b32_e32 v19, v2
	v_mov_b32_e32 v20, v2
	v_mov_b32_e32 v21, v2
	v_mov_b32_e32 v10, v2
	v_mov_b32_e32 v11, v2
	v_mov_b32_e32 v12, v2
	v_mov_b32_e32 v13, v2
	v_mov_b32_e32 v22, v2
	v_mov_b32_e32 v23, v2
	v_mov_b32_e32 v24, v2
	v_mov_b32_e32 v25, v2
	v_mov_b32_e32 v30, v2
	v_mov_b32_e32 v31, v2
	v_mov_b32_e32 v32, v2
	v_mov_b32_e32 v33, v2
	v_mov_b32_e32 v38, v2
	v_mov_b32_e32 v39, v2
	v_mov_b32_e32 v40, v2
	v_mov_b32_e32 v41, v2
	v_mov_b32_e32 v46, v2
	v_mov_b32_e32 v47, v2
	v_mov_b32_e32 v48, v2
	v_mov_b32_e32 v49, v2
	v_mov_b32_e32 v54, v2
	v_mov_b32_e32 v55, v2
	v_mov_b32_e32 v56, v2
	v_mov_b32_e32 v57, v2
	v_mov_b32_e32 v66, v2
	v_mov_b32_e32 v67, v2
	v_mov_b32_e32 v68, v2
	v_mov_b32_e32 v69, v2
	v_mov_b32_e32 v78, v2
	v_mov_b32_e32 v79, v2
	v_mov_b32_e32 v80, v2
	v_mov_b32_e32 v81, v2
	v_mov_b32_e32 v90, v2
	v_mov_b32_e32 v91, v2
	v_mov_b32_e32 v92, v2
	v_mov_b32_e32 v93, v2
	v_mov_b32_e32 v94, v2
	v_mov_b32_e32 v95, v2
	v_mov_b32_e32 v96, v2
	v_mov_b32_e32 v97, v2
	v_mov_b32_e32 v138, v2
	v_mov_b32_e32 v139, v2
	v_mov_b32_e32 v140, v2
	v_mov_b32_e32 v141, v2
	v_mov_b32_e32 v142, v2
	v_mov_b32_e32 v143, v2
	v_mov_b32_e32 v144, v2
	v_mov_b32_e32 v145, v2
	v_mov_b32_e32 v154, v2
	v_mov_b32_e32 v155, v2
	v_mov_b32_e32 v156, v2
	v_mov_b32_e32 v157, v2
	v_mov_b32_e32 v158, v2
	v_mov_b32_e32 v159, v2
	v_mov_b32_e32 v160, v2
	v_mov_b32_e32 v161, v2
	v_mov_b32_e32 v70, v2
	v_mov_b32_e32 v71, v2
	v_mov_b32_e32 v72, v2
	v_mov_b32_e32 v73, v2
	v_mov_b32_e32 v74, v2
	v_mov_b32_e32 v75, v2
	v_mov_b32_e32 v76, v2
	v_mov_b32_e32 v77, v2
	v_mov_b32_e32 v82, v2
	v_mov_b32_e32 v83, v2
	v_mov_b32_e32 v84, v2
	v_mov_b32_e32 v85, v2
	v_mov_b32_e32 v86, v2
	v_mov_b32_e32 v87, v2
	v_mov_b32_e32 v88, v2
	v_mov_b32_e32 v89, v2
	v_mov_b32_e32 v98, v2
	v_mov_b32_e32 v99, v2
	v_mov_b32_e32 v100, v2
	v_mov_b32_e32 v101, v2
	v_mov_b32_e32 v102, v2
	v_mov_b32_e32 v103, v2
	v_mov_b32_e32 v104, v2
	v_mov_b32_e32 v105, v2
	v_mov_b32_e32 v146, v2
	v_mov_b32_e32 v147, v2
	v_mov_b32_e32 v148, v2
	v_mov_b32_e32 v149, v2
	v_mov_b32_e32 v150, v2
	v_mov_b32_e32 v151, v2
	v_mov_b32_e32 v152, v2
	v_mov_b32_e32 v153, v2
	s_waitcnt vmcnt(0)
